# instruction selection in the NAT softmax: 16-value row max as a v_max3 tree without the canonicalising self-max ops (bitwise identical for non-NaN scores)
# baseline (speedup 1.0000x reference)
.LBB0_544:
	v_max3_f32 v1, v74, v75, v76
	v_max3_f32 v2, v77, v68, v69
	v_max3_f32 v3, v70, v71, v64
	v_max3_f32 v72, v65, v66, v67
	v_max3_f32 v73, v60, v61, v62
	v_max3_f32 v1, v1, v2, v63
	v_max3_f32 v3, v3, v72, v73
	v_max_f32_e32 v1, v1, v3
	s_nop 0
	v_mov_b32_e32 v2, v1
	s_nop 1
	v_permlane16_swap_b32_e32 v1, v2
	s_nop 1
	v_max_f32_e32 v1, v1, v2
	s_nop 0
	v_mov_b32_e32 v2, v1
	s_nop 1
	v_permlane32_swap_b32_e32 v1, v2
	s_nop 1
	v_max_f32_e32 v1, v1, v2
	v_mul_f32_e32 v1, s71, v1
	v_max_f32_e32 v1, v100, v1
	v_cmp_gt_f32_e32 vcc, v1, v100
	s_cbranch_vccz .LBB0_546
	v_sub_f32_e32 v2, v100, v1
	v_exp_f32_e32 v2, v2
	s_nop 0
	v_pk_mul_f32 v[26:27], v[26:27], v[2:3] op_sel_hi:[1,0]
	v_pk_mul_f32 v[24:25], v[24:25], v[2:3] op_sel_hi:[1,0]
	v_pk_mul_f32 v[22:23], v[22:23], v[2:3] op_sel_hi:[1,0]
	v_pk_mul_f32 v[20:21], v[20:21], v[2:3] op_sel_hi:[1,0]
	v_pk_mul_f32 v[18:19], v[18:19], v[2:3] op_sel_hi:[1,0]
	v_pk_mul_f32 v[16:17], v[16:17], v[2:3] op_sel_hi:[1,0]
	v_pk_mul_f32 v[14:15], v[14:15], v[2:3] op_sel_hi:[1,0]
	v_pk_mul_f32 v[12:13], v[12:13], v[2:3] op_sel_hi:[1,0]
	v_mul_f32_e32 v99, v99, v2
